# phase 4 deferred S5 item: waves 4-7 start about 1 us after waves 0-3 so the two waves of a SIMD do not run the latency-bound item prologue in lockstep
# speedup vs baseline: 1.0050x; 1.0017x over previous
.LBB0_857:
	v_ashrrev_i32_e32 v0, 6, v45
	v_lshl_add_u32 v33, s2, 3, v0
	s_waitcnt lgkmcnt(0)
	s_mov_b32 s4, s54
	s_movk_i32 s99, 0x1000
	s_cmp_eq_u32 s53, 4
	s_cbranch_scc0 .Ls5_p3
	v_add_u32_e32 v33, 0x800, v33
	v_readfirstlane_b32 s4, v0
	s_cmp_lt_u32 s4, 4
	s_cbranch_scc1 .Ls5_nostag
	s_sleep 32
.Ls5_nostag:
	s_mov_b32 s4, s54
	s_branch .Ls5_lim
